# merged-value-half attention unit + dense work-queue ids + GEMM loop trims
# baseline (speedup 1.0000x reference)
.LBB0_528:
	s_or_b64 exec, exec, s[6:7]
	v_mov_b32_e32 v0, s31
	s_waitcnt vmcnt(0) lgkmcnt(0)
	s_barrier
	ds_read_b32 v0, v0
	s_movk_i32 s1, 0x51f
	s_mov_b64 s[6:7], -1
	s_waitcnt lgkmcnt(0)
	s_barrier
	v_cmp_lt_i32_e32 vcc, s1, v0
	v_readfirstlane_b32 s0, v0
	s_cbranch_vccnz .LBB0_523
	s_cmp_lt_i32 s0, 32
	s_cselect_b64 s[56:57], -1, 0
	s_add_i32 s1, s0, 0xfffffee0
	s_cmpk_lt_u32 s1, 0x200
	s_cselect_b64 s[6:7], -1, 0
	s_or_b64 s[6:7], s[56:57], s[6:7]
	s_andn2_b64 vcc, exec, s[6:7]
	s_mov_b64 s[6:7], -1
	s_cbranch_vccz .LBB0_555
	s_lshl_b32 s46, s0, 1
	s_cmpk_lt_u32 s0, 0x120
	s_cselect_b32 s8, 64, 0x440
	s_sub_i32 s46, s46, s8
	s_cmpk_gt_u32 s46, 0x1ff
	s_cbranch_scc1 .Lam_ctx
	s_lshr_b32 s8, s46, 8
	s_bfe_u32 s9, s46, 0x30002
	s_lshl_b32 s10, s8, 11
	s_lshl_b32 s9, s9, 8
	s_add_i32 s10, s10, s9
	s_add_i32 s10, s10, 0x2000
	s_mulk_i32 s8, 0x900
	s_add_i32 s11, s8, 0x2000
	s_bfe_u32 s12, s46, 0x30005
	s_mov_b32 s13, 36
	s_branch .Lam_go

.Lam_nodma_b:
	s_sub_i32 s13, s13, 2
	s_cmp_gt_u32 s13, 0
	s_cbranch_scc1 .Lam_loop
	v_and_b32_e32 v240, 31, v96
	v_lshl_add_u32 v241, v240, 2, s50
	ds_write_b32 v241, v239 offset:128
	v_lshrrev_b32_e32 v241, 5, v96
	v_lshl_add_u32 v242, v241, 4, s50
	s_waitcnt lgkmcnt(0)
	ds_read_b128 v[212:215], v242 offset:128
	ds_read_b128 v[216:219], v242 offset:160
	ds_read_b128 v[220:223], v242 offset:192
	ds_read_b128 v[224:227], v242 offset:224
	s_lshl_b32 s37, s36, 5
	v_lshl_add_u32 v241, v241, 2, s37
	v_lshlrev_b32_e32 v241, 13, v241
	v_lshl_add_u32 v241, v240, 1, v241
	s_waitcnt lgkmcnt(0)
	v_rcp_f32_e32 v212, v212
	v_rcp_f32_e32 v213, v213
	v_rcp_f32_e32 v214, v214
	v_rcp_f32_e32 v215, v215
	v_rcp_f32_e32 v216, v216
	v_rcp_f32_e32 v217, v217
	v_rcp_f32_e32 v218, v218
	v_rcp_f32_e32 v219, v219
	v_rcp_f32_e32 v220, v220
	v_rcp_f32_e32 v221, v221
	v_rcp_f32_e32 v222, v222
	v_rcp_f32_e32 v223, v223
	v_rcp_f32_e32 v224, v224
	v_rcp_f32_e32 v225, v225
	v_rcp_f32_e32 v226, v226
	v_rcp_f32_e32 v227, v227
	s_nop 0
	v_mov_b32_e32 v240, v241
	v_mul_f32_e32 v162, v0, v212
	v_cvt_pk_bf16_f32 v162, v162, v162
	global_store_short v240, v162, s[22:23]
	v_mul_f32_e32 v163, v16, v212
	v_cvt_pk_bf16_f32 v163, v163, v163
	global_store_short v240, v163, s[22:23] offset:64
	v_mul_f32_e32 v164, v32, v212
	v_cvt_pk_bf16_f32 v164, v164, v164
	global_store_short v240, v164, s[22:23] offset:128
	v_mul_f32_e32 v165, v48, v212
	v_cvt_pk_bf16_f32 v165, v165, v165
	global_store_short v240, v165, s[22:23] offset:192
	v_mul_f32_e32 v166, v64, v212
	v_cvt_pk_bf16_f32 v166, v166, v166
	global_store_short v240, v166, s[22:23] offset:256
	v_mul_f32_e32 v167, v80, v212
	v_cvt_pk_bf16_f32 v167, v167, v167
	global_store_short v240, v167, s[22:23] offset:320
	v_mul_f32_e32 v168, v98, v212
	v_cvt_pk_bf16_f32 v168, v168, v168
	global_store_short v240, v168, s[22:23] offset:384
	v_mul_f32_e32 v169, v114, v212
	v_cvt_pk_bf16_f32 v169, v169, v169
	global_store_short v240, v169, s[22:23] offset:448
	v_add_u32_e32 v240, 0x2000, v241
	v_mul_f32_e32 v170, v1, v213
	v_cvt_pk_bf16_f32 v170, v170, v170
	global_store_short v240, v170, s[22:23]
	v_mul_f32_e32 v171, v17, v213
	v_cvt_pk_bf16_f32 v171, v171, v171
	global_store_short v240, v171, s[22:23] offset:64
	v_mul_f32_e32 v172, v33, v213
	v_cvt_pk_bf16_f32 v172, v172, v172
	global_store_short v240, v172, s[22:23] offset:128
	v_mul_f32_e32 v173, v49, v213
	v_cvt_pk_bf16_f32 v173, v173, v173
	global_store_short v240, v173, s[22:23] offset:192
	v_mul_f32_e32 v174, v65, v213
	v_cvt_pk_bf16_f32 v174, v174, v174
	global_store_short v240, v174, s[22:23] offset:256
	v_mul_f32_e32 v175, v81, v213
	v_cvt_pk_bf16_f32 v175, v175, v175
	global_store_short v240, v175, s[22:23] offset:320
	v_mul_f32_e32 v176, v99, v213
	v_cvt_pk_bf16_f32 v176, v176, v176
	global_store_short v240, v176, s[22:23] offset:384
	v_mul_f32_e32 v177, v115, v213
	v_cvt_pk_bf16_f32 v177, v177, v177
	global_store_short v240, v177, s[22:23] offset:448
	v_add_u32_e32 v240, 0x4000, v241
	v_mul_f32_e32 v178, v2, v214
	v_cvt_pk_bf16_f32 v178, v178, v178
	global_store_short v240, v178, s[22:23]
	v_mul_f32_e32 v179, v18, v214
	v_cvt_pk_bf16_f32 v179, v179, v179
	global_store_short v240, v179, s[22:23] offset:64
	v_mul_f32_e32 v180, v34, v214
	v_cvt_pk_bf16_f32 v180, v180, v180
	global_store_short v240, v180, s[22:23] offset:128
	v_mul_f32_e32 v181, v50, v214
	v_cvt_pk_bf16_f32 v181, v181, v181
	global_store_short v240, v181, s[22:23] offset:192
	v_mul_f32_e32 v182, v66, v214
	v_cvt_pk_bf16_f32 v182, v182, v182
	global_store_short v240, v182, s[22:23] offset:256
	v_mul_f32_e32 v183, v82, v214
	v_cvt_pk_bf16_f32 v183, v183, v183
	global_store_short v240, v183, s[22:23] offset:320
	v_mul_f32_e32 v184, v100, v214
	v_cvt_pk_bf16_f32 v184, v184, v184
	global_store_short v240, v184, s[22:23] offset:384
	v_mul_f32_e32 v185, v116, v214
	v_cvt_pk_bf16_f32 v185, v185, v185
	global_store_short v240, v185, s[22:23] offset:448
	v_add_u32_e32 v240, 0x6000, v241
	v_mul_f32_e32 v186, v3, v215
	v_cvt_pk_bf16_f32 v186, v186, v186
	global_store_short v240, v186, s[22:23]
	v_mul_f32_e32 v187, v19, v215
	v_cvt_pk_bf16_f32 v187, v187, v187
	global_store_short v240, v187, s[22:23] offset:64
	v_mul_f32_e32 v188, v35, v215
	v_cvt_pk_bf16_f32 v188, v188, v188
	global_store_short v240, v188, s[22:23] offset:128
	v_mul_f32_e32 v189, v51, v215
	v_cvt_pk_bf16_f32 v189, v189, v189
	global_store_short v240, v189, s[22:23] offset:192
	v_mul_f32_e32 v190, v67, v215
	v_cvt_pk_bf16_f32 v190, v190, v190
	global_store_short v240, v190, s[22:23] offset:256
	v_mul_f32_e32 v191, v83, v215
	v_cvt_pk_bf16_f32 v191, v191, v191
	global_store_short v240, v191, s[22:23] offset:320
	v_mul_f32_e32 v192, v101, v215
	v_cvt_pk_bf16_f32 v192, v192, v192
	global_store_short v240, v192, s[22:23] offset:384
	v_mul_f32_e32 v193, v117, v215
	v_cvt_pk_bf16_f32 v193, v193, v193
	global_store_short v240, v193, s[22:23] offset:448
	v_add_u32_e32 v240, 0x10000, v241
	v_mul_f32_e32 v162, v4, v216
	v_cvt_pk_bf16_f32 v162, v162, v162
	global_store_short v240, v162, s[22:23]
	v_mul_f32_e32 v163, v20, v216
	v_cvt_pk_bf16_f32 v163, v163, v163
	global_store_short v240, v163, s[22:23] offset:64
	v_mul_f32_e32 v164, v36, v216
	v_cvt_pk_bf16_f32 v164, v164, v164
	global_store_short v240, v164, s[22:23] offset:128
	v_mul_f32_e32 v165, v52, v216
	v_cvt_pk_bf16_f32 v165, v165, v165
	global_store_short v240, v165, s[22:23] offset:192
	v_mul_f32_e32 v166, v68, v216
	v_cvt_pk_bf16_f32 v166, v166, v166
	global_store_short v240, v166, s[22:23] offset:256
	v_mul_f32_e32 v167, v84, v216
	v_cvt_pk_bf16_f32 v167, v167, v167
	global_store_short v240, v167, s[22:23] offset:320
	v_mul_f32_e32 v168, v102, v216
	v_cvt_pk_bf16_f32 v168, v168, v168
	global_store_short v240, v168, s[22:23] offset:384
	v_mul_f32_e32 v169, v118, v216
	v_cvt_pk_bf16_f32 v169, v169, v169
	global_store_short v240, v169, s[22:23] offset:448
	v_add_u32_e32 v240, 0x12000, v241
	v_mul_f32_e32 v170, v5, v217
	v_cvt_pk_bf16_f32 v170, v170, v170
	global_store_short v240, v170, s[22:23]
	v_mul_f32_e32 v171, v21, v217
	v_cvt_pk_bf16_f32 v171, v171, v171
	global_store_short v240, v171, s[22:23] offset:64
	v_mul_f32_e32 v172, v37, v217
	v_cvt_pk_bf16_f32 v172, v172, v172
	global_store_short v240, v172, s[22:23] offset:128
	v_mul_f32_e32 v173, v53, v217
	v_cvt_pk_bf16_f32 v173, v173, v173
	global_store_short v240, v173, s[22:23] offset:192
	v_mul_f32_e32 v174, v69, v217
	v_cvt_pk_bf16_f32 v174, v174, v174
	global_store_short v240, v174, s[22:23] offset:256
	v_mul_f32_e32 v175, v85, v217
	v_cvt_pk_bf16_f32 v175, v175, v175
	global_store_short v240, v175, s[22:23] offset:320
	v_mul_f32_e32 v176, v103, v217
	v_cvt_pk_bf16_f32 v176, v176, v176
	global_store_short v240, v176, s[22:23] offset:384
	v_mul_f32_e32 v177, v119, v217
	v_cvt_pk_bf16_f32 v177, v177, v177
	global_store_short v240, v177, s[22:23] offset:448
	v_add_u32_e32 v240, 0x14000, v241
	v_mul_f32_e32 v178, v6, v218
	v_cvt_pk_bf16_f32 v178, v178, v178
	global_store_short v240, v178, s[22:23]
	v_mul_f32_e32 v179, v22, v218
	v_cvt_pk_bf16_f32 v179, v179, v179
	global_store_short v240, v179, s[22:23] offset:64
	v_mul_f32_e32 v180, v38, v218
	v_cvt_pk_bf16_f32 v180, v180, v180
	global_store_short v240, v180, s[22:23] offset:128
	v_mul_f32_e32 v181, v54, v218
	v_cvt_pk_bf16_f32 v181, v181, v181
	global_store_short v240, v181, s[22:23] offset:192
	v_mul_f32_e32 v182, v70, v218
	v_cvt_pk_bf16_f32 v182, v182, v182
	global_store_short v240, v182, s[22:23] offset:256
	v_mul_f32_e32 v183, v86, v218
	v_cvt_pk_bf16_f32 v183, v183, v183
	global_store_short v240, v183, s[22:23] offset:320
	v_mul_f32_e32 v184, v104, v218
	v_cvt_pk_bf16_f32 v184, v184, v184
	global_store_short v240, v184, s[22:23] offset:384
	v_mul_f32_e32 v185, v120, v218
	v_cvt_pk_bf16_f32 v185, v185, v185
	global_store_short v240, v185, s[22:23] offset:448
	v_add_u32_e32 v240, 0x16000, v241
	v_mul_f32_e32 v186, v7, v219
	v_cvt_pk_bf16_f32 v186, v186, v186
	global_store_short v240, v186, s[22:23]
	v_mul_f32_e32 v187, v23, v219
	v_cvt_pk_bf16_f32 v187, v187, v187
	global_store_short v240, v187, s[22:23] offset:64
	v_mul_f32_e32 v188, v39, v219
	v_cvt_pk_bf16_f32 v188, v188, v188
	global_store_short v240, v188, s[22:23] offset:128
	v_mul_f32_e32 v189, v55, v219
	v_cvt_pk_bf16_f32 v189, v189, v189
	global_store_short v240, v189, s[22:23] offset:192
	v_mul_f32_e32 v190, v71, v219
	v_cvt_pk_bf16_f32 v190, v190, v190
	global_store_short v240, v190, s[22:23] offset:256
	v_mul_f32_e32 v191, v87, v219
	v_cvt_pk_bf16_f32 v191, v191, v191
	global_store_short v240, v191, s[22:23] offset:320
	v_mul_f32_e32 v192, v105, v219
	v_cvt_pk_bf16_f32 v192, v192, v192
	global_store_short v240, v192, s[22:23] offset:384
	v_mul_f32_e32 v193, v121, v219
	v_cvt_pk_bf16_f32 v193, v193, v193
	global_store_short v240, v193, s[22:23] offset:448
	v_add_u32_e32 v240, 0x20000, v241
	v_mul_f32_e32 v162, v8, v220
	v_cvt_pk_bf16_f32 v162, v162, v162
	global_store_short v240, v162, s[22:23]
	v_mul_f32_e32 v163, v24, v220
	v_cvt_pk_bf16_f32 v163, v163, v163
	global_store_short v240, v163, s[22:23] offset:64
	v_mul_f32_e32 v164, v40, v220
	v_cvt_pk_bf16_f32 v164, v164, v164
	global_store_short v240, v164, s[22:23] offset:128
	v_mul_f32_e32 v165, v56, v220
	v_cvt_pk_bf16_f32 v165, v165, v165
	global_store_short v240, v165, s[22:23] offset:192
	v_mul_f32_e32 v166, v72, v220
	v_cvt_pk_bf16_f32 v166, v166, v166
	global_store_short v240, v166, s[22:23] offset:256
	v_mul_f32_e32 v167, v88, v220
	v_cvt_pk_bf16_f32 v167, v167, v167
	global_store_short v240, v167, s[22:23] offset:320
	v_mul_f32_e32 v168, v106, v220
	v_cvt_pk_bf16_f32 v168, v168, v168
	global_store_short v240, v168, s[22:23] offset:384
	v_mul_f32_e32 v169, v122, v220
	v_cvt_pk_bf16_f32 v169, v169, v169
	global_store_short v240, v169, s[22:23] offset:448
	v_add_u32_e32 v240, 0x22000, v241
	v_mul_f32_e32 v170, v9, v221
	v_cvt_pk_bf16_f32 v170, v170, v170
	global_store_short v240, v170, s[22:23]
	v_mul_f32_e32 v171, v25, v221
	v_cvt_pk_bf16_f32 v171, v171, v171
	global_store_short v240, v171, s[22:23] offset:64
	v_mul_f32_e32 v172, v41, v221
	v_cvt_pk_bf16_f32 v172, v172, v172
	global_store_short v240, v172, s[22:23] offset:128
	v_mul_f32_e32 v173, v57, v221
	v_cvt_pk_bf16_f32 v173, v173, v173
	global_store_short v240, v173, s[22:23] offset:192
	v_mul_f32_e32 v174, v73, v221
	v_cvt_pk_bf16_f32 v174, v174, v174
	global_store_short v240, v174, s[22:23] offset:256
	v_mul_f32_e32 v175, v89, v221
	v_cvt_pk_bf16_f32 v175, v175, v175
	global_store_short v240, v175, s[22:23] offset:320
	v_mul_f32_e32 v176, v107, v221
	v_cvt_pk_bf16_f32 v176, v176, v176
	global_store_short v240, v176, s[22:23] offset:384
	v_mul_f32_e32 v177, v123, v221
	v_cvt_pk_bf16_f32 v177, v177, v177
	global_store_short v240, v177, s[22:23] offset:448
	v_add_u32_e32 v240, 0x24000, v241
	v_mul_f32_e32 v178, v10, v222
	v_cvt_pk_bf16_f32 v178, v178, v178
	global_store_short v240, v178, s[22:23]
	v_mul_f32_e32 v179, v26, v222
	v_cvt_pk_bf16_f32 v179, v179, v179
	global_store_short v240, v179, s[22:23] offset:64
	v_mul_f32_e32 v180, v42, v222
	v_cvt_pk_bf16_f32 v180, v180, v180
	global_store_short v240, v180, s[22:23] offset:128
	v_mul_f32_e32 v181, v58, v222
	v_cvt_pk_bf16_f32 v181, v181, v181
	global_store_short v240, v181, s[22:23] offset:192
	v_mul_f32_e32 v182, v74, v222
	v_cvt_pk_bf16_f32 v182, v182, v182
	global_store_short v240, v182, s[22:23] offset:256
	v_mul_f32_e32 v183, v90, v222
	v_cvt_pk_bf16_f32 v183, v183, v183
	global_store_short v240, v183, s[22:23] offset:320
	v_mul_f32_e32 v184, v108, v222
	v_cvt_pk_bf16_f32 v184, v184, v184
	global_store_short v240, v184, s[22:23] offset:384
	v_mul_f32_e32 v185, v124, v222
	v_cvt_pk_bf16_f32 v185, v185, v185
	global_store_short v240, v185, s[22:23] offset:448
	v_add_u32_e32 v240, 0x26000, v241
	v_mul_f32_e32 v186, v11, v223
	v_cvt_pk_bf16_f32 v186, v186, v186
	global_store_short v240, v186, s[22:23]
	v_mul_f32_e32 v187, v27, v223
	v_cvt_pk_bf16_f32 v187, v187, v187
	global_store_short v240, v187, s[22:23] offset:64
	v_mul_f32_e32 v188, v43, v223
	v_cvt_pk_bf16_f32 v188, v188, v188
	global_store_short v240, v188, s[22:23] offset:128
	v_mul_f32_e32 v189, v59, v223
	v_cvt_pk_bf16_f32 v189, v189, v189
	global_store_short v240, v189, s[22:23] offset:192
	v_mul_f32_e32 v190, v75, v223
	v_cvt_pk_bf16_f32 v190, v190, v190
	global_store_short v240, v190, s[22:23] offset:256
	v_mul_f32_e32 v191, v91, v223
	v_cvt_pk_bf16_f32 v191, v191, v191
	global_store_short v240, v191, s[22:23] offset:320
	v_mul_f32_e32 v192, v109, v223
	v_cvt_pk_bf16_f32 v192, v192, v192
	global_store_short v240, v192, s[22:23] offset:384
	v_mul_f32_e32 v193, v125, v223
	v_cvt_pk_bf16_f32 v193, v193, v193
	global_store_short v240, v193, s[22:23] offset:448
	v_add_u32_e32 v240, 0x30000, v241
	v_mul_f32_e32 v162, v12, v224
	v_cvt_pk_bf16_f32 v162, v162, v162
	global_store_short v240, v162, s[22:23]
	v_mul_f32_e32 v163, v28, v224
	v_cvt_pk_bf16_f32 v163, v163, v163
	global_store_short v240, v163, s[22:23] offset:64
	v_mul_f32_e32 v164, v44, v224
	v_cvt_pk_bf16_f32 v164, v164, v164
	global_store_short v240, v164, s[22:23] offset:128
	v_mul_f32_e32 v165, v60, v224
	v_cvt_pk_bf16_f32 v165, v165, v165
	global_store_short v240, v165, s[22:23] offset:192
	v_mul_f32_e32 v166, v76, v224
	v_cvt_pk_bf16_f32 v166, v166, v166
	global_store_short v240, v166, s[22:23] offset:256
	v_mul_f32_e32 v167, v92, v224
	v_cvt_pk_bf16_f32 v167, v167, v167
	global_store_short v240, v167, s[22:23] offset:320
	v_mul_f32_e32 v168, v110, v224
	v_cvt_pk_bf16_f32 v168, v168, v168
	global_store_short v240, v168, s[22:23] offset:384
	v_mul_f32_e32 v169, v126, v224
	v_cvt_pk_bf16_f32 v169, v169, v169
	global_store_short v240, v169, s[22:23] offset:448
	v_add_u32_e32 v240, 0x32000, v241
	v_mul_f32_e32 v170, v13, v225
	v_cvt_pk_bf16_f32 v170, v170, v170
	global_store_short v240, v170, s[22:23]
	v_mul_f32_e32 v171, v29, v225
	v_cvt_pk_bf16_f32 v171, v171, v171
	global_store_short v240, v171, s[22:23] offset:64
	v_mul_f32_e32 v172, v45, v225
	v_cvt_pk_bf16_f32 v172, v172, v172
	global_store_short v240, v172, s[22:23] offset:128
	v_mul_f32_e32 v173, v61, v225
	v_cvt_pk_bf16_f32 v173, v173, v173
	global_store_short v240, v173, s[22:23] offset:192
	v_mul_f32_e32 v174, v77, v225
	v_cvt_pk_bf16_f32 v174, v174, v174
	global_store_short v240, v174, s[22:23] offset:256
	v_mul_f32_e32 v175, v93, v225
	v_cvt_pk_bf16_f32 v175, v175, v175
	global_store_short v240, v175, s[22:23] offset:320
	v_mul_f32_e32 v176, v111, v225
	v_cvt_pk_bf16_f32 v176, v176, v176
	global_store_short v240, v176, s[22:23] offset:384
	v_mul_f32_e32 v177, v127, v225
	v_cvt_pk_bf16_f32 v177, v177, v177
	global_store_short v240, v177, s[22:23] offset:448
	v_add_u32_e32 v240, 0x34000, v241
	v_mul_f32_e32 v178, v14, v226
	v_cvt_pk_bf16_f32 v178, v178, v178
	global_store_short v240, v178, s[22:23]
	v_mul_f32_e32 v179, v30, v226
	v_cvt_pk_bf16_f32 v179, v179, v179
	global_store_short v240, v179, s[22:23] offset:64
	v_mul_f32_e32 v180, v46, v226
	v_cvt_pk_bf16_f32 v180, v180, v180
	global_store_short v240, v180, s[22:23] offset:128
	v_mul_f32_e32 v181, v62, v226
	v_cvt_pk_bf16_f32 v181, v181, v181
	global_store_short v240, v181, s[22:23] offset:192
	v_mul_f32_e32 v182, v78, v226
	v_cvt_pk_bf16_f32 v182, v182, v182
	global_store_short v240, v182, s[22:23] offset:256
	v_mul_f32_e32 v183, v94, v226
	v_cvt_pk_bf16_f32 v183, v183, v183
	global_store_short v240, v183, s[22:23] offset:320
	v_mul_f32_e32 v184, v112, v226
	v_cvt_pk_bf16_f32 v184, v184, v184
	global_store_short v240, v184, s[22:23] offset:384
	v_mul_f32_e32 v185, v128, v226
	v_cvt_pk_bf16_f32 v185, v185, v185
	global_store_short v240, v185, s[22:23] offset:448
	v_add_u32_e32 v240, 0x36000, v241
	v_mul_f32_e32 v186, v15, v227
	v_cvt_pk_bf16_f32 v186, v186, v186
	global_store_short v240, v186, s[22:23]
	v_mul_f32_e32 v187, v31, v227
	v_cvt_pk_bf16_f32 v187, v187, v187
	global_store_short v240, v187, s[22:23] offset:64
	v_mul_f32_e32 v188, v47, v227
	v_cvt_pk_bf16_f32 v188, v188, v188
	global_store_short v240, v188, s[22:23] offset:128
	v_mul_f32_e32 v189, v63, v227
	v_cvt_pk_bf16_f32 v189, v189, v189
	global_store_short v240, v189, s[22:23] offset:192
	v_mul_f32_e32 v190, v79, v227
	v_cvt_pk_bf16_f32 v190, v190, v190
	global_store_short v240, v190, s[22:23] offset:256
	v_mul_f32_e32 v191, v95, v227
	v_cvt_pk_bf16_f32 v191, v191, v191
	global_store_short v240, v191, s[22:23] offset:320
	v_mul_f32_e32 v192, v113, v227
	v_cvt_pk_bf16_f32 v192, v192, v192
	global_store_short v240, v192, s[22:23] offset:384
	v_mul_f32_e32 v193, v129, v227
	v_cvt_pk_bf16_f32 v193, v193, v193
	global_store_short v240, v193, s[22:23] offset:448
	s_waitcnt lgkmcnt(0)
	s_barrier
	s_brev_b32 s30, 64
	v_readlane_b32 s31, v254, 63
	s_movk_i32 s61, 0x1000
	s_mov_b64 s[6:7], 0
.LBB0_555:
	s_and_b64 vcc, exec, s[6:7]
	s_cbranch_vccz .LBB0_522
	s_add_i32 s1, s0, 0xffffff00
	s_and_b64 s[6:7], s[56:57], exec
	s_cselect_b32 s6, s0, s1
	s_cmp_gt_i32 s6, 31
	s_cselect_b64 s[8:9], -1, 0
	s_sub_i32 s7, s6, 32
	s_mov_b32 s0, s93
	s_cmp_lt_i32 s6, 32
	s_cselect_b64 s[10:11], -1, 0
	v_mbcnt_lo_u32_b32 v0, -1, s0
	s_and_b64 s[0:1], s[10:11], exec
	s_cselect_b32 s0, s6, s7
	s_ashr_i32 s1, s0, 4
	s_lshl_b32 s6, s1, 3
	s_bfe_u32 s15, s0, 0x20002
	s_or_b32 s6, s6, s52
	v_mbcnt_hi_u32_b32 v0, -1, v0
	s_or_b32 s6, s6, s15
	v_or_b32_e32 v190, s84, v0
	s_bfe_u32 s14, s0, 0x10001
	s_lshl_b32 s0, s0, 8
	s_ashr_i32 s7, s6, 31
	s_and_b32 s0, s0, 0x100
	s_lshl_b64 s[6:7], s[6:7], 17
	v_and_b32_e32 v140, 15, v190
	s_and_b64 vcc, exec, s[8:9]
	s_cbranch_vccnz .LBB0_558
	v_readlane_b32 s16, v254, 54
	s_lshl_b32 s12, s14, 3
	v_readlane_b32 s17, v254, 55
	s_load_dwordx2 s[12:13], s[16:17], s12 offset:0x20
	s_lshl_b64 s[16:17], s[6:7], 2
	v_lshlrev_b32_e32 v96, 2, v140
	v_lshlrev_b32_e32 v2, 9, v190
	s_mov_b32 s30, 0x60000
	s_waitcnt lgkmcnt(0)
	s_add_u32 s12, s12, s16
	s_addc_u32 s13, s13, s17
	s_lshl_b32 s16, s0, 2
	s_add_u32 s12, s12, s16
	s_addc_u32 s13, s13, 0
	v_readlane_b32 s16, v253, 11
	v_readlane_b32 s17, v253, 12
	s_add_u32 s12, s12, s16
	s_addc_u32 s13, s13, s17
	v_lshl_add_u64 v[0:1], s[12:13], 0, v[96:97]
	v_and_b32_e32 v96, 0x6000, v2
	v_lshl_add_u64 v[98:99], v[0:1], 0, v[96:97]
	v_add_co_u32_e32 v8, vcc, s61, v98
	s_mov_b32 s12, 0x8000
	s_nop 0
	v_addc_co_u32_e32 v9, vcc, 0, v99, vcc
	global_load_dword v4, v[98:99], off
	global_load_dword v0, v[98:99], off offset:64
	global_load_dword v5, v[98:99], off offset:2048
	global_load_dword v1, v[98:99], off offset:2112
	global_load_dword v6, v[8:9], off
	global_load_dword v2, v[8:9], off offset:64
	global_load_dword v7, v[8:9], off offset:2048
	global_load_dword v3, v[8:9], off offset:2112
	v_add_co_u32_e32 v8, vcc, s12, v98
	s_mov_b32 s12, 0x9000
	s_nop 0
	v_addc_co_u32_e32 v9, vcc, 0, v99, vcc
	v_add_co_u32_e32 v10, vcc, s12, v98
	s_mov_b32 s12, 0x11000
	s_nop 0
	v_addc_co_u32_e32 v11, vcc, 0, v99, vcc
	v_add_co_u32_e32 v16, vcc, s96, v98
	global_load_dword v52, v[10:11], off offset:-4096
	global_load_dword v48, v[8:9], off offset:64
	global_load_dword v53, v[8:9], off offset:2048
	global_load_dword v54, v[10:11], off
	global_load_dword v50, v[10:11], off offset:64
	global_load_dword v55, v[10:11], off offset:2048
	global_load_dword v51, v[10:11], off offset:2112
	global_load_dword v49, v[8:9], off offset:2112
	v_addc_co_u32_e32 v17, vcc, 0, v99, vcc
	v_add_co_u32_e32 v18, vcc, s12, v98
	s_mov_b32 s12, 0x18000
	s_nop 0
	v_addc_co_u32_e32 v19, vcc, 0, v99, vcc
	global_load_dword v12, v[18:19], off offset:-4096
	global_load_dword v8, v[16:17], off offset:64
	global_load_dword v13, v[16:17], off offset:2048
	global_load_dword v14, v[18:19], off
	global_load_dword v10, v[18:19], off offset:64
	global_load_dword v15, v[18:19], off offset:2048
	global_load_dword v11, v[18:19], off offset:2112
	global_load_dword v9, v[16:17], off offset:2112
	v_add_co_u32_e32 v16, vcc, s12, v98
	s_mov_b32 s12, 0x19000
	s_nop 0
	v_addc_co_u32_e32 v17, vcc, 0, v99, vcc
	v_add_co_u32_e32 v18, vcc, s12, v98
	s_mov_b32 s12, 0x20000
	s_nop 0
	v_addc_co_u32_e32 v19, vcc, 0, v99, vcc
	v_add_co_u32_e32 v24, vcc, s12, v98
	s_mov_b32 s12, 0x21000
	s_nop 0
	v_addc_co_u32_e32 v25, vcc, 0, v99, vcc
	v_add_co_u32_e32 v26, vcc, s12, v98
	global_load_dword v36, v[18:19], off offset:-4096
	global_load_dword v32, v[16:17], off offset:64
	global_load_dword v37, v[16:17], off offset:2048
	global_load_dword v38, v[18:19], off
	global_load_dword v34, v[18:19], off offset:64
	global_load_dword v39, v[18:19], off offset:2048
	global_load_dword v35, v[18:19], off offset:2112
	global_load_dword v33, v[16:17], off offset:2112
	v_addc_co_u32_e32 v27, vcc, 0, v99, vcc
	global_load_dword v20, v[26:27], off offset:-4096
	global_load_dword v16, v[24:25], off offset:64
	global_load_dword v21, v[24:25], off offset:2048
	global_load_dword v22, v[26:27], off
	global_load_dword v18, v[26:27], off offset:64
	global_load_dword v23, v[26:27], off offset:2048
	global_load_dword v19, v[26:27], off offset:2112
	global_load_dword v17, v[24:25], off offset:2112
	v_add_co_u32_e32 v24, vcc, s75, v98
	s_mov_b32 s12, 0x31000
	s_nop 0
	v_addc_co_u32_e32 v25, vcc, 0, v99, vcc
	v_add_co_u32_e32 v26, vcc, s2, v98
	s_nop 1
	v_addc_co_u32_e32 v27, vcc, 0, v99, vcc
	v_add_co_u32_e32 v40, vcc, s91, v98
	global_load_dword v60, v[26:27], off offset:-4096
	global_load_dword v56, v[24:25], off offset:64
	global_load_dword v61, v[24:25], off offset:2048
	global_load_dword v62, v[26:27], off
	global_load_dword v58, v[26:27], off offset:64
	global_load_dword v63, v[26:27], off offset:2048
	global_load_dword v59, v[26:27], off offset:2112
	global_load_dword v57, v[24:25], off offset:2112
	v_addc_co_u32_e32 v41, vcc, 0, v99, vcc
	v_add_co_u32_e32 v42, vcc, s12, v98
	s_mov_b32 s12, 0x38000
	s_nop 0
	v_addc_co_u32_e32 v43, vcc, 0, v99, vcc
	global_load_dword v28, v[42:43], off offset:-4096
	global_load_dword v24, v[40:41], off offset:64
	global_load_dword v29, v[40:41], off offset:2048
	global_load_dword v30, v[42:43], off
	global_load_dword v26, v[42:43], off offset:64
	global_load_dword v31, v[42:43], off offset:2048
	global_load_dword v27, v[42:43], off offset:2112
	global_load_dword v25, v[40:41], off offset:2112
	v_add_co_u32_e32 v40, vcc, s12, v98
	s_mov_b32 s12, 0x39000
	s_nop 0
	v_addc_co_u32_e32 v41, vcc, 0, v99, vcc
	v_add_co_u32_e32 v42, vcc, s12, v98
	s_mov_b32 s12, 0x40000
	s_nop 0
	v_addc_co_u32_e32 v43, vcc, 0, v99, vcc
	v_add_co_u32_e32 v64, vcc, s12, v98
	s_mov_b32 s12, 0x41000
	s_nop 0
	v_addc_co_u32_e32 v65, vcc, 0, v99, vcc
	v_add_co_u32_e32 v66, vcc, s12, v98
	global_load_dword v76, v[42:43], off offset:-4096
	global_load_dword v72, v[40:41], off offset:64
	global_load_dword v77, v[40:41], off offset:2048
	global_load_dword v78, v[42:43], off
	global_load_dword v74, v[42:43], off offset:64
	global_load_dword v79, v[42:43], off offset:2048
	global_load_dword v75, v[42:43], off offset:2112
	global_load_dword v73, v[40:41], off offset:2112
	v_addc_co_u32_e32 v67, vcc, 0, v99, vcc
	s_mov_b32 s12, 0x48000
	global_load_dword v44, v[66:67], off offset:-4096
	global_load_dword v40, v[64:65], off offset:64
	global_load_dword v45, v[64:65], off offset:2048
	global_load_dword v46, v[66:67], off
	global_load_dword v42, v[66:67], off offset:64
	global_load_dword v47, v[66:67], off offset:2048
	global_load_dword v43, v[66:67], off offset:2112
	global_load_dword v41, v[64:65], off offset:2112
	v_add_co_u32_e32 v64, vcc, s12, v98
	s_mov_b32 s12, 0x49000
	s_nop 0
	v_addc_co_u32_e32 v65, vcc, 0, v99, vcc
	v_add_co_u32_e32 v66, vcc, s12, v98
	s_mov_b32 s12, 0x58000
	s_nop 0
	v_addc_co_u32_e32 v67, vcc, 0, v99, vcc
	v_add_co_u32_e32 v80, vcc, s70, v98
	global_load_dword v100, v[66:67], off offset:-4096
	global_load_dword v88, v[64:65], off offset:64
	global_load_dword v101, v[64:65], off offset:2048
	global_load_dword v102, v[66:67], off
	global_load_dword v90, v[66:67], off offset:64
	global_load_dword v103, v[66:67], off offset:2048
	global_load_dword v91, v[66:67], off offset:2112
	global_load_dword v89, v[64:65], off offset:2112
	v_addc_co_u32_e32 v81, vcc, 0, v99, vcc
	v_add_co_u32_e32 v82, vcc, s51, v98
	s_nop 1
	v_addc_co_u32_e32 v83, vcc, 0, v99, vcc
	global_load_dword v68, v[82:83], off offset:-4096
	global_load_dword v64, v[80:81], off offset:64
	global_load_dword v69, v[80:81], off offset:2048
	global_load_dword v70, v[82:83], off
	global_load_dword v66, v[82:83], off offset:64
	global_load_dword v71, v[82:83], off offset:2048
	global_load_dword v67, v[82:83], off offset:2112
	global_load_dword v65, v[80:81], off offset:2112
	v_add_co_u32_e32 v80, vcc, s12, v98
	s_mov_b32 s12, 0x59000
	s_nop 0
	v_addc_co_u32_e32 v81, vcc, 0, v99, vcc
	v_add_co_u32_e32 v82, vcc, s12, v98
	s_mov_b32 s12, 0x61000
	s_nop 0
	v_addc_co_u32_e32 v83, vcc, 0, v99, vcc
	v_add_co_u32_e32 v92, vcc, s30, v98
	global_load_dword v112, v[82:83], off offset:-4096
	global_load_dword v108, v[80:81], off offset:64
	global_load_dword v113, v[80:81], off offset:2048
	global_load_dword v114, v[82:83], off
	global_load_dword v110, v[82:83], off offset:64
	global_load_dword v115, v[82:83], off offset:2048
	global_load_dword v111, v[82:83], off offset:2112
	global_load_dword v109, v[80:81], off offset:2112
	v_addc_co_u32_e32 v93, vcc, 0, v99, vcc
	v_add_co_u32_e32 v94, vcc, s12, v98
	s_mov_b32 s12, 0x68000
	s_nop 0
	v_addc_co_u32_e32 v95, vcc, 0, v99, vcc
	global_load_dword v84, v[94:95], off offset:-4096
	global_load_dword v80, v[92:93], off offset:64
	global_load_dword v85, v[92:93], off offset:2048
	global_load_dword v86, v[94:95], off
	global_load_dword v82, v[94:95], off offset:64
	global_load_dword v87, v[94:95], off offset:2048
	global_load_dword v83, v[94:95], off offset:2112
	global_load_dword v81, v[92:93], off offset:2112
	v_add_co_u32_e32 v92, vcc, s12, v98
	s_mov_b32 s12, 0x69000
	s_nop 0
	v_addc_co_u32_e32 v93, vcc, 0, v99, vcc
	v_add_co_u32_e32 v94, vcc, s12, v98
	s_mov_b32 s12, 0x70000
	s_nop 0
	v_addc_co_u32_e32 v95, vcc, 0, v99, vcc
	v_add_co_u32_e32 v124, vcc, s12, v98
	s_mov_b32 s12, 0x71000
	s_nop 0
	v_addc_co_u32_e32 v125, vcc, 0, v99, vcc
	v_add_co_u32_e32 v126, vcc, s12, v98
	global_load_dword v120, v[94:95], off offset:-4096
	global_load_dword v116, v[92:93], off offset:64
	global_load_dword v121, v[92:93], off offset:2048
	global_load_dword v122, v[94:95], off
	global_load_dword v118, v[94:95], off offset:64
	global_load_dword v123, v[94:95], off offset:2048
	global_load_dword v119, v[94:95], off offset:2112
	global_load_dword v117, v[92:93], off offset:2112
	v_addc_co_u32_e32 v127, vcc, 0, v99, vcc
	global_load_dword v104, v[126:127], off offset:-4096
	global_load_dword v92, v[124:125], off offset:64
	global_load_dword v105, v[124:125], off offset:2048
	global_load_dword v106, v[126:127], off
	global_load_dword v94, v[126:127], off offset:64
	global_load_dword v107, v[126:127], off offset:2048
	global_load_dword v95, v[126:127], off offset:2112
	global_load_dword v93, v[124:125], off offset:2112
	v_add_co_u32_e32 v126, vcc, s60, v98
	s_nop 1
	v_addc_co_u32_e32 v127, vcc, 0, v99, vcc
	v_add_co_u32_e32 v98, vcc, 0x79000, v98
	s_nop 1
	v_addc_co_u32_e32 v99, vcc, 0, v99, vcc
	global_load_dword v124, v[126:127], off
	global_load_dword v128, v[126:127], off offset:64
	global_load_dword v125, v[126:127], off offset:2048
	global_load_dword v129, v[126:127], off offset:2112
	s_nop 0
	global_load_dword v126, v[98:99], off
	global_load_dword v130, v[98:99], off offset:64
	global_load_dword v127, v[98:99], off offset:2048
	global_load_dword v131, v[98:99], off offset:2112
	s_branch .LBB0_559
